# MLA body A: row-sum adds and P packs of the previous tile spread under the 12 QK MFMAs, V transposed reads issued right after last K reads; copy-movs removed (sum into separate register)
# baseline (speedup 1.0000x reference)
; __device__ __forceinline__ void finishSM(f32x16& p0, f32x16& p1, float alpha, float& l_reg, bf16x8& pa0, bf16x8& pa1, bf16x8& pa2, bf16x8& pa3) {
; #pragma unroll
;   for (int r = 0; r < 16; ++r) p1[r] = __builtin_amdgcn_exp2f(p1[r]);
;   float ps = 0;
; #pragma unroll
;   for (int r = 0; r < 16; ++r) ps += p0[r];
; #pragma unroll
;   for (int r = 0; r < 16; ++r) ps += p1[r];
;   { auto rr = __builtin_amdgcn_permlane32_swap(__float_as_uint(ps), __float_as_uint(ps), false, false);
;     ps = __uint_as_float(rr[0]) + __uint_as_float(rr[1]); }
;   l_reg = l_reg * alpha + ps;
;     ...
;   PK4(p0, 0, pa0); PK4(p0, 8, pa1); PK4(p1, 0, pa2); PK4(p1, 8, pa3);
; template <int DQK> __device__ __forceinline__ void qkt(f32x16& p0, f32x16& p1, const char* Ks, const bf16x8* qr, int r32, int hi) {
;   p0 = f32x16{}; p1 = f32x16{};
; #pragma unroll
;   for (int d0 = 0; d0 < DQK / 16; ++d0) { int cb = (d0 * 16 + hi * 8) * 2;
;     bf16x8 b0 = *reinterpret_cast<const bf16x8*>(Ks + KSWZ(r32, cb));
;     bf16x8 b1 = *reinterpret_cast<const bf16x8*>(Ks + KSWZ(32 + r32, cb));
;     p0 = __builtin_amdgcn_mfma_f32_32x32x16_bf16(b0, qr[d0], p0, 0, 0, 0);
;     p1 = __builtin_amdgcn_mfma_f32_32x32x16_bf16(b1, qr[d0], p1, 0, 0, 0); }
; }
.LBB0_300:
	s_add_i32 s25, s11, -3
	s_cmp_lg_u32 s32, 0
	s_cbranch_scc1 .Lmy_h1B
	ds_read_b128 v[32:35], v148 offset:49152
	ds_read_b128 v[36:39], v148 offset:57344
	ds_read_b128 v[164:167], v152 offset:49152
	ds_read_b128 v[168:171], v152 offset:57344
	s_waitcnt lgkmcnt(3)
	v_mfma_f32_32x32x16_bf16 v[48:63], v[32:35], v[84:87], v[210:225]
	v_add_f32_e32 v155, v126, v160
	v_add_f32_e32 v155, v127, v155
	v_cvt_pk_bf16_f32 v200, v126, v160
	v_add_f32_e32 v155, v161, v155
	s_waitcnt lgkmcnt(2)
	v_mfma_f32_32x32x16_bf16 v[32:47], v[36:39], v[84:87], v[210:225]
	v_add_f32_e32 v155, v158, v155
	v_cvt_pk_bf16_f32 v201, v127, v161
	v_add_f32_e32 v155, v162, v155
	v_add_f32_e32 v155, v159, v155
	s_waitcnt lgkmcnt(1)
	v_mfma_f32_32x32x16_bf16 v[48:63], v[164:167], v[80:83], v[48:63]
	v_cvt_pk_bf16_f32 v202, v158, v162
	v_add_f32_e32 v155, v163, v155
	v_add_f32_e32 v155, v118, v155
	v_cvt_pk_bf16_f32 v203, v159, v163
	s_waitcnt lgkmcnt(0)
	v_mfma_f32_32x32x16_bf16 v[32:47], v[168:171], v[80:83], v[32:47]
	ds_read_b128 v[164:167], v151 offset:49152
	ds_read_b128 v[168:171], v151 offset:57344
	v_add_f32_e32 v155, v121, v155
	v_add_f32_e32 v155, v119, v155
	v_cvt_pk_bf16_f32 v226, v118, v121
	v_add_f32_e32 v155, v122, v155
	s_waitcnt lgkmcnt(1)
	v_mfma_f32_32x32x16_bf16 v[48:63], v[164:167], v[76:79], v[48:63]
	v_add_f32_e32 v155, v120, v155
	v_cvt_pk_bf16_f32 v227, v119, v122
	v_add_f32_e32 v155, v123, v155
	v_add_f32_e32 v155, v124, v155
	s_waitcnt lgkmcnt(0)
	v_mfma_f32_32x32x16_bf16 v[32:47], v[168:171], v[76:79], v[32:47]
	ds_read_b128 v[164:167], v149 offset:49152
	ds_read_b128 v[168:171], v149 offset:57344
	v_cvt_pk_bf16_f32 v228, v120, v123
	v_add_f32_e32 v155, v125, v155
	v_add_f32_e32 v155, v114, v155
	v_cvt_pk_bf16_f32 v229, v124, v125
	s_waitcnt lgkmcnt(1)
	v_mfma_f32_32x32x16_bf16 v[48:63], v[164:167], v[72:75], v[48:63]
	v_add_f32_e32 v155, v115, v155
	v_add_f32_e32 v155, v112, v155
	v_cvt_pk_bf16_f32 v230, v114, v115
	v_add_f32_e32 v155, v113, v155
	s_waitcnt lgkmcnt(0)
	v_mfma_f32_32x32x16_bf16 v[32:47], v[168:171], v[72:75], v[32:47]
	ds_read_b128 v[164:167], v150 offset:49152
	ds_read_b128 v[168:171], v150 offset:57344
	v_add_f32_e32 v155, v108, v155
	v_cvt_pk_bf16_f32 v231, v112, v113
	v_add_f32_e32 v155, v109, v155
	v_add_f32_e32 v155, v104, v155
	s_waitcnt lgkmcnt(1)
	v_mfma_f32_32x32x16_bf16 v[48:63], v[164:167], v[68:71], v[48:63]
	v_cvt_pk_bf16_f32 v232, v108, v109
	v_add_f32_e32 v155, v105, v155
	v_add_f32_e32 v155, v102, v155
	v_cvt_pk_bf16_f32 v233, v104, v105
	s_waitcnt lgkmcnt(0)
	v_mfma_f32_32x32x16_bf16 v[32:47], v[168:171], v[68:71], v[32:47]
	ds_read_b128 v[164:167], v153 offset:49152
	ds_read_b128 v[168:171], v153 offset:57344
	ds_read_b64_tr_b16 v[184:185], v144 offset:0
	ds_read_b64_tr_b16 v[186:187], v144 offset:0x800
	ds_read_b64_tr_b16 v[188:189], v144 offset:0x1000
	ds_read_b64_tr_b16 v[190:191], v144 offset:0x1800
	ds_read_b64_tr_b16 v[192:193], v144 offset:0x2000
	ds_read_b64_tr_b16 v[194:195], v144 offset:0x2800
	ds_read_b64_tr_b16 v[196:197], v144 offset:0x3000
	ds_read_b64_tr_b16 v[198:199], v144 offset:0x3800
	v_add_f32_e32 v155, v103, v155
	v_add_f32_e32 v155, v110, v155
	v_cvt_pk_bf16_f32 v136, v102, v103
	v_add_f32_e32 v155, v111, v155
	s_waitcnt vmcnt(0)
	ds_write_b128 v146, v[88:91] offset:32768
	ds_write_b128 v147, v[96:99] offset:32768
	ds_write_b128 v145, v[92:95] offset:16384
	s_waitcnt lgkmcnt(12)
	v_mfma_f32_32x32x16_bf16 v[48:63], v[164:167], v[64:67], v[48:63]
	v_add_f32_e32 v155, v106, v155
	v_cvt_pk_bf16_f32 v137, v110, v111
	v_add_f32_e32 v155, v107, v155
	v_add_f32_e32 v155, v100, v155
	s_waitcnt lgkmcnt(11)
	v_mfma_f32_32x32x16_bf16 v[32:47], v[168:171], v[64:67], v[32:47]
	v_cvt_pk_bf16_f32 v138, v106, v107
	v_add_f32_e32 v155, v101, v155
	v_cvt_pk_bf16_f32 v139, v100, v101
	s_lshl_b32 s0, s11, 6
	s_cmpk_lt_u32 s25, 0x7e
	s_cselect_b32 s1, s10, s24
	s_add_i32 s1, s1, s0
	s_addk_i32 s1, 0xffc0
	s_mul_i32 s1, s1, 0x300
	s_add_u32 s12, s18, s1
	s_addc_u32 s13, s19, 0
	s_cmpk_lt_u32 s25, 0x7f
	s_cselect_b32 s98, s10, s24
	s_add_i32 s98, s98, s0
	s_addk_i32 s98, 0xff80
	s_lshl_b32 s98, s98, 9
	s_add_u32 s98, s20, s98
	s_addc_u32 s99, s21, 0
	global_load_dwordx4 v[100:103], v134, s[12:13]
	global_load_dwordx4 v[108:111], v135, s[98:99]
	global_load_dwordx4 v[104:107], v238, s[12:13] offset:128
	s_waitcnt lgkmcnt(0)
	s_nop 0
	v_mfma_f32_32x32x16_bf16 v[0:15], v[200:203], v[184:187], v[0:15]
	ds_read_b64_tr_b16 v[184:185], v144 offset:0x200
	ds_read_b64_tr_b16 v[186:187], v144 offset:0xa00
	v_max_f32_e32 v112, v48, v49
	v_max3_f32 v112, v112, v50, v51
	v_max3_f32 v112, v112, v52, v53
	v_max3_f32 v112, v112, v54, v55
	v_max3_f32 v112, v112, v56, v57
	v_mfma_f32_32x32x16_bf16 v[0:15], v[226:229], v[188:191], v[0:15]
	ds_read_b64_tr_b16 v[188:189], v144 offset:0x1200
	ds_read_b64_tr_b16 v[190:191], v144 offset:0x1a00
	v_max3_f32 v112, v112, v58, v59
	v_max3_f32 v112, v112, v60, v61
	v_max3_f32 v112, v112, v62, v63
	v_max3_f32 v112, v112, v32, v33
	v_max3_f32 v112, v112, v34, v35
	v_mfma_f32_32x32x16_bf16 v[0:15], v[230:233], v[192:195], v[0:15]
	ds_read_b64_tr_b16 v[192:193], v144 offset:0x2200
	ds_read_b64_tr_b16 v[194:195], v144 offset:0x2a00
	v_max3_f32 v112, v112, v36, v37
	v_max3_f32 v112, v112, v38, v39
	v_max3_f32 v112, v112, v40, v41
	v_max3_f32 v112, v112, v42, v43
	v_max3_f32 v112, v112, v44, v45
	v_mfma_f32_32x32x16_bf16 v[0:15], v[136:139], v[196:199], v[0:15]
	ds_read_b64_tr_b16 v[196:197], v144 offset:0x3200
	ds_read_b64_tr_b16 v[198:199], v144 offset:0x3a00
	v_max3_f32 v112, v112, v46, v47
	v_cmp_ge_f32_e32 vcc, s80, v112
	s_cmp_eq_u64 vcc, exec
	s_cbranch_scc0 .Lmy_rare_a1
	v_mov_b32_e32 v157, 1.0
	s_mov_b64 vcc, 0

; __device__ __forceinline__ void finishSM(f32x16& p0, f32x16& p1, float alpha, float& l_reg, bf16x8& pa0, bf16x8& pa1, bf16x8& pa2, bf16x8& pa3) {
; #pragma unroll
;   for (int r = 0; r < 16; ++r) p1[r] = __builtin_amdgcn_exp2f(p1[r]);
;   float ps = 0;
; #pragma unroll
;   for (int r = 0; r < 16; ++r) ps += p0[r];
; #pragma unroll
;   for (int r = 0; r < 16; ++r) ps += p1[r];
;   { auto rr = __builtin_amdgcn_permlane32_swap(__float_as_uint(ps), __float_as_uint(ps), false, false);
;     ps = __uint_as_float(rr[0]) + __uint_as_float(rr[1]); }
;   l_reg = l_reg * alpha + ps;
;     ...
;   PK4(p0, 0, pa0); PK4(p0, 8, pa1); PK4(p1, 0, pa2); PK4(p1, 8, pa3);
; template <int DQK> __device__ __forceinline__ void qkt(f32x16& p0, f32x16& p1, const char* Ks, const bf16x8* qr, int r32, int hi) {
;   p0 = f32x16{}; p1 = f32x16{};
; #pragma unroll
;   for (int d0 = 0; d0 < DQK / 16; ++d0) { int cb = (d0 * 16 + hi * 8) * 2;
;     bf16x8 b0 = *reinterpret_cast<const bf16x8*>(Ks + KSWZ(r32, cb));
;     bf16x8 b1 = *reinterpret_cast<const bf16x8*>(Ks + KSWZ(32 + r32, cb));
;     p0 = __builtin_amdgcn_mfma_f32_32x32x16_bf16(b0, qr[d0], p0, 0, 0, 0);
;     p1 = __builtin_amdgcn_mfma_f32_32x32x16_bf16(b1, qr[d0], p1, 0, 0, 0); }
; }
.LBB0_304:
	s_waitcnt lgkmcnt(0)
	s_barrier
	ds_read_b128 v[32:35], v148 offset:32768
	ds_read_b128 v[36:39], v148 offset:40960
	ds_read_b128 v[176:179], v152 offset:32768
	ds_read_b128 v[180:183], v152 offset:40960
	s_waitcnt lgkmcnt(3)
	v_mfma_f32_32x32x16_bf16 v[48:63], v[32:35], v[84:87], v[210:225]
	v_add_f32_e32 v156, v112, v127
	v_add_f32_e32 v156, v113, v156
	v_cvt_pk_bf16_f32 v200, v112, v127
	v_add_f32_e32 v156, v126, v156
	s_waitcnt lgkmcnt(2)
	v_mfma_f32_32x32x16_bf16 v[32:47], v[36:39], v[84:87], v[210:225]
	v_add_f32_e32 v156, v114, v156
	v_cvt_pk_bf16_f32 v201, v113, v126
	v_add_f32_e32 v156, v125, v156
	v_add_f32_e32 v156, v115, v156
	s_waitcnt lgkmcnt(1)
	v_mfma_f32_32x32x16_bf16 v[48:63], v[176:179], v[80:83], v[48:63]
	v_cvt_pk_bf16_f32 v202, v114, v125
	v_add_f32_e32 v156, v124, v156
	v_add_f32_e32 v156, v116, v156
	v_cvt_pk_bf16_f32 v203, v115, v124
	s_waitcnt lgkmcnt(0)
	v_mfma_f32_32x32x16_bf16 v[32:47], v[180:183], v[80:83], v[32:47]
	ds_read_b128 v[176:179], v151 offset:32768
	ds_read_b128 v[180:183], v151 offset:40960
	v_add_f32_e32 v156, v123, v156
	v_add_f32_e32 v156, v117, v156
	v_cvt_pk_bf16_f32 v226, v116, v123
	v_add_f32_e32 v156, v122, v156
	s_waitcnt lgkmcnt(1)
	v_mfma_f32_32x32x16_bf16 v[48:63], v[176:179], v[76:79], v[48:63]
	v_add_f32_e32 v156, v118, v156
	v_cvt_pk_bf16_f32 v227, v117, v122
	v_add_f32_e32 v156, v121, v156
	v_add_f32_e32 v156, v119, v156
	s_waitcnt lgkmcnt(0)
	v_mfma_f32_32x32x16_bf16 v[32:47], v[180:183], v[76:79], v[32:47]
	ds_read_b128 v[176:179], v149 offset:32768
	ds_read_b128 v[180:183], v149 offset:40960
	v_cvt_pk_bf16_f32 v228, v118, v121
	v_add_f32_e32 v156, v120, v156
	v_add_f32_e32 v156, v167, v156
	v_cvt_pk_bf16_f32 v229, v119, v120
	s_waitcnt lgkmcnt(1)
	v_mfma_f32_32x32x16_bf16 v[48:63], v[176:179], v[72:75], v[48:63]
	v_add_f32_e32 v156, v168, v156
	v_add_f32_e32 v156, v169, v156
	v_cvt_pk_bf16_f32 v230, v167, v168
	v_add_f32_e32 v156, v170, v156
	s_waitcnt lgkmcnt(0)
	v_mfma_f32_32x32x16_bf16 v[32:47], v[180:183], v[72:75], v[32:47]
	ds_read_b128 v[176:179], v150 offset:32768
	ds_read_b128 v[180:183], v150 offset:40960
	v_add_f32_e32 v156, v171, v156
	v_cvt_pk_bf16_f32 v231, v169, v170
	v_add_f32_e32 v156, v172, v156
	v_add_f32_e32 v156, v160, v156
	s_waitcnt lgkmcnt(1)
	v_mfma_f32_32x32x16_bf16 v[48:63], v[176:179], v[68:71], v[48:63]
	v_cvt_pk_bf16_f32 v232, v171, v172
	v_add_f32_e32 v156, v161, v156
	v_add_f32_e32 v156, v162, v156
	v_cvt_pk_bf16_f32 v233, v160, v161
	s_waitcnt lgkmcnt(0)
	v_mfma_f32_32x32x16_bf16 v[32:47], v[180:183], v[68:71], v[32:47]
	ds_read_b128 v[176:179], v153 offset:32768
	ds_read_b128 v[180:183], v153 offset:40960
	ds_read_b64_tr_b16 v[184:185], v143 offset:0
	ds_read_b64_tr_b16 v[186:187], v143 offset:0x800
	ds_read_b64_tr_b16 v[188:189], v143 offset:0x1000
	ds_read_b64_tr_b16 v[190:191], v143 offset:0x1800
	ds_read_b64_tr_b16 v[192:193], v143 offset:0x2000
	ds_read_b64_tr_b16 v[194:195], v143 offset:0x2800
	ds_read_b64_tr_b16 v[196:197], v143 offset:0x3000
	ds_read_b64_tr_b16 v[198:199], v143 offset:0x3800
	v_add_f32_e32 v156, v163, v156
	v_add_f32_e32 v156, v164, v156
	v_cvt_pk_bf16_f32 v136, v162, v163
	v_add_f32_e32 v156, v165, v156
	s_waitcnt vmcnt(0)
	ds_write_b128 v146, v[100:103] offset:49152
	ds_write_b128 v147, v[104:107] offset:49152
	ds_write_b128 v145, v[108:111]
	s_waitcnt lgkmcnt(12)
	v_mfma_f32_32x32x16_bf16 v[48:63], v[176:179], v[64:67], v[48:63]
	v_add_f32_e32 v156, v166, v156
	v_cvt_pk_bf16_f32 v137, v164, v165
	v_add_f32_e32 v156, v173, v156
	v_add_f32_e32 v156, v174, v156
	s_waitcnt lgkmcnt(11)
	v_mfma_f32_32x32x16_bf16 v[32:47], v[180:183], v[64:67], v[32:47]
	v_cvt_pk_bf16_f32 v138, v166, v173
	v_add_f32_e32 v156, v159, v156
	v_cvt_pk_bf16_f32 v139, v174, v159
	s_lshl_b32 s0, s11, 6
	s_cmpk_lt_u32 s25, 0x7e
	s_cselect_b32 s98, s10, s24
	s_add_i32 s98, s98, s0
	s_addk_i32 s98, 0xffc0
	s_lshl_b32 s98, s98, 9
	s_add_u32 s98, s20, s98
	s_addc_u32 s99, s21, 0
	global_load_dwordx4 v[92:95], v135, s[98:99]
	s_cmpk_gt_u32 s25, 0x80
	s_cbranch_scc1 .LBB0_306
	s_cmpk_lt_u32 s25, 0x7d
	s_cselect_b32 s1, s10, s24
	s_add_i32 s1, s1, s0
	s_mul_i32 s1, s1, 0x300
	s_add_u32 s12, s18, s1
	s_addc_u32 s13, s19, 0
	global_load_dwordx4 v[88:91], v134, s[12:13]
	global_load_dwordx4 v[96:99], v238, s[12:13] offset:128

; template <int DQK> __device__ __forceinline__ void partialSM(f32x16& p0, f32x16& p1, float& m_reg, float& mn, float& alpha) {
;     ...
;   for (int r = 0; r < 16; ++r) p0[r] = __builtin_amdgcn_exp2f(p0[r]);
; }
; __device__ __forceinline__ void finishSM(f32x16& p0, f32x16& p1, float alpha, float& l_reg, bf16x8& pa0, bf16x8& pa1, bf16x8& pa2, bf16x8& pa3) {
; #pragma unroll
;   for (int r = 0; r < 16; ++r) p1[r] = __builtin_amdgcn_exp2f(p1[r]);
;   float ps = 0;
; #pragma unroll
;   for (int r = 0; r < 16; ++r) ps += p0[r];
; #pragma unroll
;   for (int r = 0; r < 16; ++r) ps += p1[r];
;   { auto rr = __builtin_amdgcn_permlane32_swap(__float_as_uint(ps), __float_as_uint(ps), false, false);
;     ps = __uint_as_float(rr[0]) + __uint_as_float(rr[1]); }
;   l_reg = l_reg * alpha + ps;
.Lmy_join_a2:
	s_waitcnt lgkmcnt(0)
	v_mfma_f32_32x32x16_bf16 v[16:31], v[200:203], v[184:187], v[16:31]
	v_exp_f32_e32 v126, v48
	v_exp_f32_e32 v160, v49
	v_exp_f32_e32 v127, v50
	v_exp_f32_e32 v161, v51
	v_exp_f32_e32 v158, v52
	v_exp_f32_e32 v162, v53
	v_exp_f32_e32 v159, v54
	v_exp_f32_e32 v163, v55
	v_exp_f32_e32 v118, v56
	v_mfma_f32_32x32x16_bf16 v[16:31], v[226:229], v[188:191], v[16:31]
	v_exp_f32_e32 v121, v57
	v_exp_f32_e32 v119, v58
	v_exp_f32_e32 v122, v59
	v_exp_f32_e32 v120, v60
	v_exp_f32_e32 v123, v61
	v_exp_f32_e32 v124, v62
	v_exp_f32_e32 v125, v63
	v_exp_f32_e32 v114, v32
	v_exp_f32_e32 v115, v33
	v_mfma_f32_32x32x16_bf16 v[16:31], v[230:233], v[192:195], v[16:31]
	v_exp_f32_e32 v112, v34
	v_exp_f32_e32 v113, v35
	v_exp_f32_e32 v108, v36
	v_exp_f32_e32 v109, v37
	v_exp_f32_e32 v104, v38
	v_exp_f32_e32 v105, v39
	v_exp_f32_e32 v102, v40
	v_exp_f32_e32 v103, v41
	v_exp_f32_e32 v110, v42
	v_mfma_f32_32x32x16_bf16 v[16:31], v[136:139], v[196:199], v[16:31]
	v_exp_f32_e32 v111, v43
	v_exp_f32_e32 v106, v44
	v_exp_f32_e32 v107, v45
	v_exp_f32_e32 v101, v47
	v_exp_f32_e32 v100, v46
	v_fmac_f32_e32 v155, v154, v142
	v_fma_f32 v142, v155, v157, v156
	s_cbranch_vccz .LBB0_310
	s_and_saveexec_b64 s[12:13], s[4:5]
	ds_write_b32 v141, v117 offset:128
	s_or_b64 exec, exec, s[12:13]
	s_waitcnt lgkmcnt(0)
	ds_read_b128 v[184:187], v129 offset:224
	ds_read_b128 v[188:191], v129 offset:192
	ds_read_b128 v[192:195], v129 offset:160
	ds_read_b128 v[196:199], v129 offset:128
	s_waitcnt lgkmcnt(3)
	v_pk_mul_f32 v[14:15], v[14:15], v[186:187]
	s_waitcnt lgkmcnt(2)
	v_pk_mul_f32 v[10:11], v[10:11], v[190:191]
	s_waitcnt lgkmcnt(1)
	v_pk_mul_f32 v[6:7], v[6:7], v[194:195]
	s_waitcnt lgkmcnt(0)
	v_pk_mul_f32 v[2:3], v[2:3], v[198:199]
	v_pk_mul_f32 v[12:13], v[12:13], v[184:185]
	v_pk_mul_f32 v[8:9], v[8:9], v[188:189]
	v_pk_mul_f32 v[4:5], v[4:5], v[192:193]
	v_pk_mul_f32 v[0:1], v[0:1], v[196:197]
	v_pk_mul_f32 v[30:31], v[30:31], v[186:187]
	v_pk_mul_f32 v[26:27], v[26:27], v[190:191]
	v_pk_mul_f32 v[22:23], v[22:23], v[194:195]
	v_pk_mul_f32 v[18:19], v[18:19], v[198:199]
	v_pk_mul_f32 v[28:29], v[28:29], v[184:185]
	v_pk_mul_f32 v[24:25], v[24:25], v[188:189]
	v_pk_mul_f32 v[20:21], v[20:21], v[192:193]
	v_pk_mul_f32 v[16:17], v[16:17], v[196:197]

; #define SBAR() __builtin_amdgcn_sched_barrier(0)
; #define SLOAD(i, j) do { const long kr_ = KROW(j); sr_[i].vs0 = ld8(Vp + (kr_ + sr) * ldv + sc); sr_[i].ks0 = ld8(Kp + (kr_ + sr) * ldk + sc); \
;     if (DQK == 96) sr_[i].ks1 = ld8(Kp + (kr_ + sr2) * ldk + sc2); } while (0)
; #define BIAS(P0, P1, j) do { if (MODE == 1) { SBAR(); if ((j) >= nA) na_bias(P0, P1, na, rs0 + (j) - nA, hi); SBAR(); } } while (0)
; __device__ __forceinline__ void finishSM(f32x16& p0, f32x16& p1, float alpha, float& l_reg, bf16x8& pa0, bf16x8& pa1, bf16x8& pa2, bf16x8& pa3) {
; #pragma unroll
;   for (int r = 0; r < 16; ++r) p1[r] = __builtin_amdgcn_exp2f(p1[r]);
;   float ps = 0;
; #pragma unroll
;   for (int r = 0; r < 16; ++r) ps += p0[r];
; #pragma unroll
;   for (int r = 0; r < 16; ++r) ps += p1[r];
;   { auto rr = __builtin_amdgcn_permlane32_swap(__float_as_uint(ps), __float_as_uint(ps), false, false);
;     ps = __uint_as_float(rr[0]) + __uint_as_float(rr[1]); }
;   l_reg = l_reg * alpha + ps;
;     ...
;   PK4(p0, 0, pa0); PK4(p0, 8, pa1); PK4(p1, 0, pa2); PK4(p1, 8, pa3);
; template <int DQK, int MODE, int ldq, int ldk, int ldv> ...
;     ...
;     SBAR(); qkt<DQK>(pB0, pB1, K_lds + SHM_K, qr, r32, hi);
;     finishSM(pA0, pA1, alA, l_reg, pa0, pa1, pa2, pa3); SBAR();
;     SLOAD(SO, j + 2); SBAR();
;     pv_d0(o, vb0, pa0, pa1, pa2, pa3); BIAS(pB0, pB1, j); partialSM<DQK>(pB0, pB1, m_reg, mnB, alB);
.Lmy_h1B:
	s_waitcnt vmcnt(0)
	ds_write_b128 v146, v[88:91] offset:32768
	ds_write_b128 v145, v[92:95] offset:16384
	v_cvt_pk_bf16_f32 v200, v126, v160
	v_cvt_pk_bf16_f32 v201, v127, v161
	v_cvt_pk_bf16_f32 v202, v158, v162
	v_cvt_pk_bf16_f32 v203, v159, v163
	v_cvt_pk_bf16_f32 v226, v118, v121
	v_cvt_pk_bf16_f32 v227, v119, v122
	v_cvt_pk_bf16_f32 v228, v120, v123
	v_cvt_pk_bf16_f32 v229, v124, v125
	v_cvt_pk_bf16_f32 v230, v114, v115
	v_cvt_pk_bf16_f32 v231, v112, v113
	v_cvt_pk_bf16_f32 v232, v108, v109
	v_cvt_pk_bf16_f32 v233, v104, v105
	v_cvt_pk_bf16_f32 v136, v102, v103
	v_cvt_pk_bf16_f32 v137, v110, v111
	v_cvt_pk_bf16_f32 v138, v106, v107
	v_cvt_pk_bf16_f32 v139, v100, v101
	v_add_f32_e32 v155, v126, v160
	v_add_f32_e32 v155, v127, v155
	v_add_f32_e32 v155, v161, v155
	v_add_f32_e32 v155, v158, v155
	v_add_f32_e32 v155, v162, v155
	v_add_f32_e32 v155, v159, v155
	v_add_f32_e32 v155, v163, v155
	v_add_f32_e32 v155, v118, v155
	v_add_f32_e32 v155, v121, v155
	v_add_f32_e32 v155, v119, v155
	v_add_f32_e32 v155, v122, v155
	v_add_f32_e32 v155, v120, v155
	v_add_f32_e32 v155, v123, v155
	v_add_f32_e32 v155, v124, v155
	v_add_f32_e32 v155, v125, v155
	v_add_f32_e32 v155, v114, v155
	v_add_f32_e32 v155, v115, v155
	v_add_f32_e32 v155, v112, v155
	v_add_f32_e32 v155, v113, v155
	v_add_f32_e32 v155, v108, v155
	v_add_f32_e32 v155, v109, v155
	v_add_f32_e32 v155, v104, v155
	v_add_f32_e32 v155, v105, v155
	v_add_f32_e32 v155, v102, v155
	v_add_f32_e32 v155, v103, v155
	v_add_f32_e32 v155, v110, v155
	v_add_f32_e32 v155, v111, v155
	v_add_f32_e32 v155, v106, v155
	v_add_f32_e32 v155, v107, v155
	v_add_f32_e32 v155, v100, v155
	v_add_f32_e32 v155, v101, v155
	s_lshl_b32 s0, s11, 6
	s_cmpk_lt_u32 s25, 0x7e
	s_cselect_b32 s1, s10, s24
	s_add_i32 s1, s1, s0
	s_addk_i32 s1, 0xffc0
	s_mul_i32 s1, s1, 0x300
	s_add_u32 s12, s18, s1
	s_addc_u32 s13, s19, 0
	s_cmpk_lt_u32 s25, 0x7f
	s_cselect_b32 s98, s10, s24
	s_add_i32 s98, s98, s0
	s_addk_i32 s98, 0xff80
	s_lshl_b32 s98, s98, 9
	s_add_u32 s98, s20, s98
	s_addc_u32 s99, s21, 0
	global_load_dwordx4 v[100:103], v134, s[12:13]
	global_load_dwordx4 v[108:111], v135, s[98:99]
	ds_read_b64_tr_b16 v[184:185], v144 offset:0
	ds_read_b64_tr_b16 v[186:187], v144 offset:0x800
	ds_read_b64_tr_b16 v[188:189], v144 offset:0x1000
	ds_read_b64_tr_b16 v[190:191], v144 offset:0x1800
	ds_read_b64_tr_b16 v[192:193], v144 offset:0x2000
	ds_read_b64_tr_b16 v[194:195], v144 offset:0x2800
	ds_read_b64_tr_b16 v[196:197], v144 offset:0x3000
	ds_read_b64_tr_b16 v[198:199], v144 offset:0x3800
	s_waitcnt lgkmcnt(0)
	s_nop 0
	v_mfma_f32_32x32x16_bf16 v[0:15], v[200:203], v[184:187], v[0:15]
	ds_read_b64_tr_b16 v[184:185], v144 offset:0x200
	ds_read_b64_tr_b16 v[186:187], v144 offset:0xa00
	v_mfma_f32_32x32x16_bf16 v[0:15], v[226:229], v[188:191], v[0:15]
	ds_read_b64_tr_b16 v[188:189], v144 offset:0x1200
	ds_read_b64_tr_b16 v[190:191], v144 offset:0x1a00
	v_mfma_f32_32x32x16_bf16 v[0:15], v[230:233], v[192:195], v[0:15]
	ds_read_b64_tr_b16 v[192:193], v144 offset:0x2200
	ds_read_b64_tr_b16 v[194:195], v144 offset:0x2a00
	v_mfma_f32_32x32x16_bf16 v[0:15], v[136:139], v[196:199], v[0:15]
	ds_read_b64_tr_b16 v[196:197], v144 offset:0x3200
	ds_read_b64_tr_b16 v[198:199], v144 offset:0x3a00
	s_waitcnt lgkmcnt(0)
	v_mfma_f32_32x32x16_bf16 v[16:31], v[200:203], v[184:187], v[16:31]
	v_mfma_f32_32x32x16_bf16 v[16:31], v[226:229], v[188:191], v[16:31]
	v_mfma_f32_32x32x16_bf16 v[16:31], v[230:233], v[192:195], v[16:31]
	v_mfma_f32_32x32x16_bf16 v[16:31], v[136:139], v[196:199], v[16:31]
	ds_read_b128 v[32:35], v148 offset:49152
	ds_read_b128 v[36:39], v148 offset:57344
	ds_read_b128 v[164:167], v152 offset:49152
	ds_read_b128 v[168:171], v152 offset:57344
	s_waitcnt lgkmcnt(3)
	v_mfma_f32_32x32x16_bf16 v[48:63], v[32:35], v[84:87], v[210:225]
	s_waitcnt lgkmcnt(2)
	v_mfma_f32_32x32x16_bf16 v[32:47], v[36:39], v[84:87], v[210:225]
	s_waitcnt lgkmcnt(1)
	v_mfma_f32_32x32x16_bf16 v[48:63], v[164:167], v[80:83], v[48:63]
	s_waitcnt lgkmcnt(0)
	v_mfma_f32_32x32x16_bf16 v[32:47], v[168:171], v[80:83], v[32:47]
	ds_read_b128 v[164:167], v151 offset:49152
	ds_read_b128 v[168:171], v151 offset:57344
	s_waitcnt lgkmcnt(1)
	v_mfma_f32_32x32x16_bf16 v[48:63], v[164:167], v[76:79], v[48:63]
	s_waitcnt lgkmcnt(0)
	v_mfma_f32_32x32x16_bf16 v[32:47], v[168:171], v[76:79], v[32:47]
	ds_read_b128 v[164:167], v149 offset:49152
	ds_read_b128 v[168:171], v149 offset:57344
	s_waitcnt lgkmcnt(1)
	v_mfma_f32_32x32x16_bf16 v[48:63], v[164:167], v[72:75], v[48:63]
	s_waitcnt lgkmcnt(0)
	v_mfma_f32_32x32x16_bf16 v[32:47], v[168:171], v[72:75], v[32:47]
	ds_read_b128 v[164:167], v150 offset:49152
	ds_read_b128 v[168:171], v150 offset:57344
	s_waitcnt lgkmcnt(1)
	v_mfma_f32_32x32x16_bf16 v[48:63], v[164:167], v[68:71], v[48:63]
	s_waitcnt lgkmcnt(0)
	v_mfma_f32_32x32x16_bf16 v[32:47], v[168:171], v[68:71], v[32:47]
	ds_read_b128 v[164:167], v153 offset:49152
	ds_read_b128 v[168:171], v153 offset:57344
	s_waitcnt lgkmcnt(1)
	v_mfma_f32_32x32x16_bf16 v[48:63], v[164:167], v[64:67], v[48:63]
	s_waitcnt lgkmcnt(0)
	v_mfma_f32_32x32x16_bf16 v[32:47], v[168:171], v[64:67], v[32:47]
	s_nop 7
	s_nop 4
	v_max_f32_e32 v112, v48, v49
	v_max3_f32 v112, v112, v50, v51
	v_max3_f32 v112, v112, v52, v53
	v_max3_f32 v112, v112, v54, v55
	v_max3_f32 v112, v112, v56, v57
	v_max3_f32 v112, v112, v58, v59
	v_max3_f32 v112, v112, v60, v61
	v_max3_f32 v112, v112, v62, v63
	v_max3_f32 v112, v112, v32, v33
	v_max3_f32 v112, v112, v34, v35
	v_max3_f32 v112, v112, v36, v37
	v_max3_f32 v112, v112, v38, v39
	v_max3_f32 v112, v112, v40, v41
	v_max3_f32 v112, v112, v42, v43
	v_max3_f32 v112, v112, v44, v45
	v_max3_f32 v112, v112, v46, v47
	v_cmp_ge_f32_e32 vcc, s80, v112
	s_cmp_eq_u64 vcc, exec
	s_cbranch_scc0 .Lmy_rare_b1
	v_mov_b32_e32 v157, 1.0
	s_mov_b64 vcc, 0

; #define SBAR() __builtin_amdgcn_sched_barrier(0)
; #define SLOAD(i, j) do { const long kr_ = KROW(j); sr_[i].vs0 = ld8(Vp + (kr_ + sr) * ldv + sc); sr_[i].ks0 = ld8(Kp + (kr_ + sr) * ldk + sc); \
;     if (DQK == 96) sr_[i].ks1 = ld8(Kp + (kr_ + sr2) * ldk + sc2); } while (0)
; __device__ __forceinline__ void finishSM(f32x16& p0, f32x16& p1, float alpha, float& l_reg, bf16x8& pa0, bf16x8& pa1, bf16x8& pa2, bf16x8& pa3) {
; #pragma unroll
;   for (int r = 0; r < 16; ++r) p1[r] = __builtin_amdgcn_exp2f(p1[r]);
;   float ps = 0;
; #pragma unroll
;   for (int r = 0; r < 16; ++r) ps += p0[r];
; #pragma unroll
;   for (int r = 0; r < 16; ++r) ps += p1[r];
;   { auto rr = __builtin_amdgcn_permlane32_swap(__float_as_uint(ps), __float_as_uint(ps), false, false);
;     ps = __uint_as_float(rr[0]) + __uint_as_float(rr[1]); }
;   l_reg = l_reg * alpha + ps;
;     ...
;   PK4(p0, 0, pa0); PK4(p0, 8, pa1); PK4(p1, 0, pa2); PK4(p1, 8, pa3);
; template <int DQK, int MODE, int ldq, int ldk, int ldv> ...
;     ...
;     SBAR(); qkt<DQK>(pA0, pA1, K_lds, qr, r32, hi);
;     finishSM(pB0, pB1, alB, l_reg, pa0, pa1, pa2, pa3); SBAR();
;     if (j + 3 < NT) SLOAD(SE, j + 3); SBAR();
.Lmy_h1B_304:
	s_waitcnt lgkmcnt(0)
	s_barrier
	s_waitcnt vmcnt(0)
	ds_write_b128 v146, v[100:103] offset:49152
	ds_write_b128 v145, v[108:111]
	v_cvt_pk_bf16_f32 v200, v112, v127
	v_cvt_pk_bf16_f32 v201, v113, v126
	v_cvt_pk_bf16_f32 v202, v114, v125
	v_cvt_pk_bf16_f32 v203, v115, v124
	v_cvt_pk_bf16_f32 v226, v116, v123
	v_cvt_pk_bf16_f32 v227, v117, v122
	v_cvt_pk_bf16_f32 v228, v118, v121
	v_cvt_pk_bf16_f32 v229, v119, v120
	v_cvt_pk_bf16_f32 v230, v167, v168
	v_cvt_pk_bf16_f32 v231, v169, v170
	v_cvt_pk_bf16_f32 v232, v171, v172
	v_cvt_pk_bf16_f32 v233, v160, v161
	v_cvt_pk_bf16_f32 v136, v162, v163
	v_cvt_pk_bf16_f32 v137, v164, v165
	v_cvt_pk_bf16_f32 v138, v166, v173
	v_cvt_pk_bf16_f32 v139, v174, v159
	v_add_f32_e32 v156, v112, v127
	v_add_f32_e32 v156, v113, v156
	v_add_f32_e32 v156, v126, v156
	v_add_f32_e32 v156, v114, v156
	v_add_f32_e32 v156, v125, v156
	v_add_f32_e32 v156, v115, v156
	v_add_f32_e32 v156, v124, v156
	v_add_f32_e32 v156, v116, v156
	v_add_f32_e32 v156, v123, v156
	v_add_f32_e32 v156, v117, v156
	v_add_f32_e32 v156, v122, v156
	v_add_f32_e32 v156, v118, v156
	v_add_f32_e32 v156, v121, v156
	v_add_f32_e32 v156, v119, v156
	v_add_f32_e32 v156, v120, v156
	v_add_f32_e32 v156, v167, v156
	v_add_f32_e32 v156, v168, v156
	v_add_f32_e32 v156, v169, v156
	v_add_f32_e32 v156, v170, v156
	v_add_f32_e32 v156, v171, v156
	v_add_f32_e32 v156, v172, v156
	v_add_f32_e32 v156, v160, v156
	v_add_f32_e32 v156, v161, v156
	v_add_f32_e32 v156, v162, v156
	v_add_f32_e32 v156, v163, v156
	v_add_f32_e32 v156, v164, v156
	v_add_f32_e32 v156, v165, v156
	v_add_f32_e32 v156, v166, v156
	v_add_f32_e32 v156, v173, v156
	v_add_f32_e32 v156, v174, v156
	v_add_f32_e32 v156, v159, v156
	s_lshl_b32 s0, s11, 6
	s_cmpk_lt_u32 s25, 0x7e
	s_cselect_b32 s98, s10, s24
	s_add_i32 s98, s98, s0
	s_addk_i32 s98, 0xffc0
	s_lshl_b32 s98, s98, 9
	s_add_u32 s98, s20, s98
	s_addc_u32 s99, s21, 0
	global_load_dwordx4 v[92:95], v135, s[98:99]
	s_cmpk_gt_u32 s25, 0x80
	s_cbranch_scc1 .Lmy_h2B_306
	s_cmpk_lt_u32 s25, 0x7d
	s_cselect_b32 s1, s10, s24
	s_add_i32 s1, s1, s0
	s_mul_i32 s1, s1, 0x300
	s_add_u32 s12, s18, s1
	s_addc_u32 s13, s19, 0
	global_load_dwordx4 v[88:91], v134, s[12:13]

; template <int DQK> __device__ __forceinline__ void partialSM(f32x16& p0, f32x16& p1, float& m_reg, float& mn, float& alpha) {
;     ...
;   for (int r = 0; r < 16; ++r) p0[r] = __builtin_amdgcn_exp2f(p0[r]);
; }
; __device__ __forceinline__ void finishSM(f32x16& p0, f32x16& p1, float alpha, float& l_reg, bf16x8& pa0, bf16x8& pa1, bf16x8& pa2, bf16x8& pa3) {
; #pragma unroll
;   for (int r = 0; r < 16; ++r) p1[r] = __builtin_amdgcn_exp2f(p1[r]);
;   float ps = 0;
; #pragma unroll
;   for (int r = 0; r < 16; ++r) ps += p0[r];
; #pragma unroll
;   for (int r = 0; r < 16; ++r) ps += p1[r];
;   { auto rr = __builtin_amdgcn_permlane32_swap(__float_as_uint(ps), __float_as_uint(ps), false, false);
;     ps = __uint_as_float(rr[0]) + __uint_as_float(rr[1]); }
;   l_reg = l_reg * alpha + ps;
.Lmy_join_b2:
	v_exp_f32_e32 v126, v48
	v_exp_f32_e32 v160, v49
	v_exp_f32_e32 v127, v50
	v_exp_f32_e32 v161, v51
	v_exp_f32_e32 v158, v52
	v_exp_f32_e32 v162, v53
	v_exp_f32_e32 v159, v54
	v_exp_f32_e32 v163, v55
	v_exp_f32_e32 v118, v56
	v_exp_f32_e32 v121, v57
	v_exp_f32_e32 v119, v58
	v_exp_f32_e32 v122, v59
	v_exp_f32_e32 v120, v60
	v_exp_f32_e32 v123, v61
	v_exp_f32_e32 v124, v62
	v_exp_f32_e32 v125, v63
	v_exp_f32_e32 v114, v32
	v_exp_f32_e32 v115, v33
	v_exp_f32_e32 v112, v34
	v_exp_f32_e32 v113, v35
	v_exp_f32_e32 v108, v36
	v_exp_f32_e32 v109, v37
	v_exp_f32_e32 v104, v38
	v_exp_f32_e32 v105, v39
	v_exp_f32_e32 v102, v40
	v_exp_f32_e32 v103, v41
	v_exp_f32_e32 v110, v42
	v_exp_f32_e32 v111, v43
	v_exp_f32_e32 v106, v44
	v_exp_f32_e32 v107, v45
	v_exp_f32_e32 v101, v47
	v_exp_f32_e32 v100, v46
	v_fmac_f32_e32 v155, v154, v142
	v_fma_f32 v142, v155, v157, v156
	s_cbranch_vccz .Lmy_h2B_310
	s_and_saveexec_b64 s[12:13], s[4:5]
	ds_write_b32 v141, v117 offset:128
	s_or_b64 exec, exec, s[12:13]
	s_waitcnt lgkmcnt(0)
	ds_read_b128 v[184:187], v129 offset:224
	ds_read_b128 v[188:191], v129 offset:192
	ds_read_b128 v[192:195], v129 offset:160
	ds_read_b128 v[196:199], v129 offset:128
	s_waitcnt lgkmcnt(3)
	v_pk_mul_f32 v[14:15], v[14:15], v[186:187]
	s_waitcnt lgkmcnt(2)
	v_pk_mul_f32 v[10:11], v[10:11], v[190:191]
	s_waitcnt lgkmcnt(1)
	v_pk_mul_f32 v[6:7], v[6:7], v[194:195]
	s_waitcnt lgkmcnt(0)
	v_pk_mul_f32 v[2:3], v[2:3], v[198:199]
	v_pk_mul_f32 v[12:13], v[12:13], v[184:185]
	v_pk_mul_f32 v[8:9], v[8:9], v[188:189]
	v_pk_mul_f32 v[4:5], v[4:5], v[192:193]
	v_pk_mul_f32 v[0:1], v[0:1], v[196:197]
	v_pk_mul_f32 v[30:31], v[30:31], v[186:187]
	v_pk_mul_f32 v[26:27], v[26:27], v[190:191]
	v_pk_mul_f32 v[22:23], v[22:23], v[194:195]
	v_pk_mul_f32 v[18:19], v[18:19], v[198:199]
	v_pk_mul_f32 v[28:29], v[28:29], v[184:185]
	v_pk_mul_f32 v[24:25], v[24:25], v[188:189]
	v_pk_mul_f32 v[20:21], v[20:21], v[192:193]
	v_pk_mul_f32 v[16:17], v[16:17], v[196:197]
